# MoE GEMM phases: expert lookup by one 32-lane compare+popcount, cnt from an LDS copy, K-loop waits no longer drain the just-issued list loads
# speedup vs baseline: 1.1398x; 1.0091x over previous
; #define TIDX tid_opaque()
; DI void moe_prefix(const Params& P, int l, int* tb) {
;   __syncthreads();
;   if (TIDX == 0) { int s = 0; for (int e = 0; e < 32; e++) { tb[e] = s; s += (P.cnt[l * 32 + e] + 255) >> 8; } tb[32] = s; }
;   __syncthreads();
; }
.LBB0_560:
	s_or_b64 exec, exec, s[0:1]
	v_mov_b32_e32 v16, v172
	v_mov_b32_e32 v0, v172
	s_barrier
	s_barrier
	v_readlane_b32 s4, v253, 63
	v_readlane_b32 s5, v255, 0
	s_lshl_b32 s2, s22, 7
	s_add_u32 s4, s4, s2
	s_addc_u32 s5, s5, 0
	v_and_b32_e32 v1, 31, v172
	v_lshlrev_b32_e32 v1, 2, v1
	global_load_dword v2, v1, s[4:5]
	v_add_u32_e32 v1, 0x24000, v1
	s_waitcnt vmcnt(0)
	ds_write_b32 v1, v2
	s_nop 0
	v_cmp_eq_u32_e32 vcc, 0, v0
	s_and_saveexec_b64 s[0:1], vcc
	s_cbranch_execz .LBB0_562
	s_lshl_b32 s84, s22, 5
	s_lshl_b64 s[2:3], s[84:85], 2
	v_readlane_b32 s4, v253, 63
	v_readlane_b32 s5, v255, 0
	s_add_u32 s2, s4, s2
	s_addc_u32 s3, s5, s3
	global_load_dwordx4 v[0:3], v149, s[2:3] offset:48
	global_load_dwordx4 v[4:7], v149, s[2:3] offset:32
	global_load_dwordx4 v[8:11], v149, s[2:3] offset:16
	global_load_dwordx4 v[12:15], v149, s[2:3]
	v_mov_b32_e32 v18, v149
	v_mov_b32_e32 v17, 0x26040
	s_waitcnt vmcnt(3)
	v_add_u32_e32 v0, 0xff, v0
	s_waitcnt vmcnt(2)
	v_add_u32_e32 v4, 0xff, v4
	s_waitcnt vmcnt(1)
	v_add_u32_e32 v8, 0xff, v8
	s_waitcnt vmcnt(0)
	v_add_u32_e32 v12, 0xff, v12
	v_ashrrev_i32_e32 v19, 8, v12
	v_add_u32_e32 v12, 0xff, v13
	v_ashrrev_i32_e32 v12, 8, v12
	v_add_u32_e32 v20, v12, v19
	v_add_u32_e32 v12, 0xff, v14
	v_ashrrev_i32_e32 v12, 8, v12
	v_add_u32_e32 v21, v12, v20
	v_mov_b32_e32 v12, 0x26000
	ds_write_b128 v12, v[18:21]
	v_add_u32_e32 v12, 0xff, v15
	v_ashrrev_i32_e32 v12, 8, v12
	v_add_u32_e32 v12, v12, v21
	v_ashrrev_i32_e32 v8, 8, v8
	v_add_u32_e32 v13, v8, v12
	v_add_u32_e32 v8, 0xff, v9
	v_ashrrev_i32_e32 v8, 8, v8
	v_add_u32_e32 v14, v8, v13
	v_add_u32_e32 v8, 0xff, v10
	v_ashrrev_i32_e32 v8, 8, v8
	v_add_u32_e32 v15, v8, v14
	v_mov_b32_e32 v8, 0x26010
	ds_write_b128 v8, v[12:15]
	v_add_u32_e32 v8, 0xff, v11
	v_ashrrev_i32_e32 v8, 8, v8
	v_add_u32_e32 v8, v8, v15
	v_ashrrev_i32_e32 v4, 8, v4
	v_add_u32_e32 v9, v4, v8
	v_add_u32_e32 v4, 0xff, v5
	v_ashrrev_i32_e32 v4, 8, v4
	v_add_u32_e32 v10, v4, v9
	v_add_u32_e32 v4, 0xff, v6
	v_ashrrev_i32_e32 v4, 8, v4
	v_add_u32_e32 v11, v4, v10
	v_mov_b32_e32 v4, 0x26020
	ds_write_b128 v4, v[8:11]
	v_add_u32_e32 v4, 0xff, v7
	v_ashrrev_i32_e32 v4, 8, v4
	v_add_u32_e32 v4, v4, v11
	v_ashrrev_i32_e32 v0, 8, v0
	v_add_u32_e32 v5, v0, v4
	v_add_u32_e32 v0, 0xff, v1
	v_ashrrev_i32_e32 v0, 8, v0
	v_add_u32_e32 v6, v0, v5
	v_add_u32_e32 v0, 0xff, v2
	v_ashrrev_i32_e32 v0, 8, v0
	v_add_u32_e32 v7, v0, v6
	v_mov_b32_e32 v0, 0x26030
	ds_write_b128 v0, v[4:7]
	v_add_u32_e32 v0, 0xff, v3
	v_ashrrev_i32_e32 v0, 8, v0
	v_add_u32_e32 v12, v0, v7
	global_load_dwordx4 v[0:3], v149, s[2:3] offset:112
	global_load_dwordx4 v[4:7], v149, s[2:3] offset:96
	global_load_dwordx4 v[8:11], v149, s[2:3] offset:80
	global_load_dwordx4 v[18:21], v149, s[2:3] offset:64
	s_waitcnt vmcnt(3)
	v_add_u32_e32 v0, 0xff, v0
	s_waitcnt vmcnt(2)
	v_add_u32_e32 v4, 0xff, v4
	s_waitcnt vmcnt(1)
	v_add_u32_e32 v8, 0xff, v8
	s_waitcnt vmcnt(0)
	v_add_u32_e32 v13, 0xff, v18
	v_ashrrev_i32_e32 v13, 8, v13
	v_add_u32_e32 v14, 0xff, v19
	v_add_u32_e32 v13, v13, v12
	v_ashrrev_i32_e32 v14, 8, v14
	v_add_u32_e32 v15, 0xff, v20
	v_add_u32_e32 v14, v14, v13
	v_ashrrev_i32_e32 v15, 8, v15
	v_add_u32_e32 v15, v15, v14
	ds_write_b128 v17, v[12:15]
	v_add_u32_e32 v12, 0xff, v21
	v_ashrrev_i32_e32 v12, 8, v12
	v_add_u32_e32 v12, v12, v15
	v_ashrrev_i32_e32 v8, 8, v8
	v_add_u32_e32 v13, v8, v12
	v_add_u32_e32 v8, 0xff, v9
	v_ashrrev_i32_e32 v8, 8, v8
	v_add_u32_e32 v14, v8, v13
	v_add_u32_e32 v8, 0xff, v10
	v_ashrrev_i32_e32 v8, 8, v8
	v_add_u32_e32 v15, v8, v14
	v_mov_b32_e32 v8, 0x26050
	ds_write_b128 v8, v[12:15]
	v_add_u32_e32 v8, 0xff, v11
	v_ashrrev_i32_e32 v8, 8, v8
	v_add_u32_e32 v8, v8, v15
	v_ashrrev_i32_e32 v4, 8, v4
	v_add_u32_e32 v9, v4, v8
	v_add_u32_e32 v4, 0xff, v5
	v_ashrrev_i32_e32 v4, 8, v4
	v_add_u32_e32 v10, v4, v9
	v_add_u32_e32 v4, 0xff, v6
	v_ashrrev_i32_e32 v4, 8, v4
	v_add_u32_e32 v11, v4, v10
	v_mov_b32_e32 v4, 0x26060
	ds_write_b128 v4, v[8:11]
	v_add_u32_e32 v4, 0xff, v7
	v_ashrrev_i32_e32 v4, 8, v4
	v_add_u32_e32 v4, v4, v11
	v_ashrrev_i32_e32 v0, 8, v0
	v_add_u32_e32 v5, v0, v4
	v_add_u32_e32 v0, 0xff, v1
	v_ashrrev_i32_e32 v0, 8, v0
	v_add_u32_e32 v6, v0, v5
	v_add_u32_e32 v0, 0xff, v2
	v_ashrrev_i32_e32 v0, 8, v0
	v_add_u32_e32 v7, v0, v6
	v_mov_b32_e32 v0, 0x26070
	ds_write_b128 v0, v[4:7]
	v_add_u32_e32 v0, 0xff, v3
	v_ashrrev_i32_e32 v0, 8, v0
	v_add_u32_e32 v0, v0, v7
	v_mov_b32_e32 v1, 0x26080
	ds_write_b32 v1, v0

; DI void moe_e1_phase(const Params& P, int l, char* smem, int* tb) {
;     ...
;   auto setup = [&](int rt, int nt, int (&tok)[8], const half_t*& w1, const half_t*& w3) {
;     int e = 0;
;     while (tb[e + 1] <= rt) e++;
;     const int rl = rt - tb[e], cnt = P.cnt[l * 32 + e];
;     const int* lst = P.list + (size_t)e * LCAP;
;     w1 = P.Wt1 + ((size_t)(l * 32 + e) * 512 + nt * 64) * 1024 + sc;
;     w3 = P.Wt3 + ((size_t)(l * 32 + e) * 512 + nt * 64) * 1024 + sc;
; #pragma unroll
;     for (int i = 0; i < 8; i++) tok[i] = lst[min(rl * 256 + i * 32 + srow, cnt - 1)] >> 1;
;   };
.LBB0_563:
	s_and_b32 s0, s3, 0x7ffffff8
	s_add_i32 s21, s0, s78
	s_cmp_lt_i32 s2, s11
	s_cselect_b64 s[0:1], -1, 0
	s_and_b64 s[6:7], s[0:1], exec
	s_cselect_b32 s4, s21, s4
	s_cmp_ge_i32 s4, s10
	s_cselect_b64 s[6:7], -1, 0
	s_and_b64 s[6:7], s[0:1], s[6:7]
	s_add_i32 s20, s20, 1
	s_add_i32 s3, s3, 32
	s_add_i32 s2, s2, 8
	s_and_b64 vcc, exec, s[6:7]
	s_cbranch_vccnz .LBB0_563
	s_andn2_b64 vcc, exec, s[0:1]
	s_cbranch_vccnz .LBB0_591
	s_mov_b32 s22, s36
	v_and_b32_e32 v0, 31, v172
	v_lshlrev_b32_e32 v0, 2, v0
	v_add_u32_e32 v0, 0x26004, v0
	ds_read_b32 v0, v0
	s_waitcnt lgkmcnt(0)
	v_cmp_ge_i32_e32 vcc, s21, v0
	s_bcnt1_i32_b32 s0, vcc_lo
	s_lshl_b32 s1, s0, 2
	s_add_i32 s1, s1, 0x26000
.LBB0_566:
	v_readlane_b32 s2, v255, 26
	s_lshl_b32 s23, s2, 5
	v_readlane_b32 s3, v255, 27
	s_add_i32 s84, s0, s23
	s_lshl_b64 s[2:3], s[84:85], 2
	v_readlane_b32 s4, v253, 63
	v_readlane_b32 s5, v255, 0
	s_add_u32 s2, s4, s2
	s_addc_u32 s3, s5, s3
	s_lshl_b32 s2, s0, 2
	s_add_i32 s2, s2, 0x24000
	v_mov_b32_e32 v3, s2
	ds_read_b32 v3, v3
	v_mov_b32_e32 v2, s1
	ds_read_b32 v2, v2
	v_ashrrev_i32_e32 v24, 3, v16
	s_mul_hi_u32 s1, s0, 0x84000
	s_mul_i32 s0, s0, 0x84000
	v_readlane_b32 s2, v255, 24
	s_waitcnt lgkmcnt(0)
	v_sub_u32_e32 v2, s21, v2
	v_lshlrev_b32_e32 v4, 8, v2
	v_add_u32_e32 v2, v4, v24
	v_readlane_b32 s3, v255, 25
	s_add_u32 s0, s2, s0
	s_addc_u32 s1, s3, s1
	v_add_u32_e32 v26, 32, v24
	v_add_u32_e32 v78, 64, v24
	v_add_u32_e32 v79, 0x60, v24
	v_add_u32_e32 v80, 0x80, v24
	v_add_u32_e32 v81, 0xa0, v24
	v_add_u32_e32 v82, 0xc0, v24
	v_add_u32_e32 v83, 0xe0, v24
	s_lshl_b32 s2, s22, 6
	v_lshrrev_b32_e32 v54, 4, v1
	s_ashr_i32 s3, s2, 31
	s_lshl_b64 s[4:5], s[84:85], 20
	v_readlane_b32 s6, v253, 53
	v_xor_b32_e32 v0, v54, v1
	s_add_u32 s6, s6, s4
	v_readlane_b32 s7, v253, 54
	v_lshlrev_b32_e32 v0, 3, v0
	s_addc_u32 s7, s7, s5
	s_lshl_b64 s[2:3], s[2:3], 11
	v_and_b32_e32 v0, 56, v0
	s_add_u32 s6, s6, s2
	s_addc_u32 s7, s7, s3
	v_lshlrev_b32_e32 v148, 1, v0
	v_lshl_add_u64 v[28:29], s[6:7], 0, v[148:149]
	v_readlane_b32 s6, v253, 55
	s_add_u32 s4, s6, s4
	v_readlane_b32 s6, v253, 56
	s_addc_u32 s5, s6, s5
	s_add_u32 s2, s4, s2
	s_addc_u32 s3, s5, s3
	v_lshl_add_u64 v[30:31], s[2:3], 0, v[148:149]
	v_readlane_b32 s2, v255, 58
	v_readlane_b32 s3, v255, 59
	v_ashrrev_i32_e32 v25, 31, v24
	v_lshlrev_b64 v[48:49], 11, v[24:25]
	v_ashrrev_i32_e32 v27, 31, v26
	v_lshlrev_b64 v[50:51], 11, v[26:27]
	v_lshl_add_u64 v[56:57], v[30:31], 0, v[50:51]
	v_bitop3_b32 v1, v54, 7, v1 bitop3:0x48
	s_waitcnt lgkmcnt(0)
	v_add_u32_e32 v5, -1, v3
	v_min_i32_e32 v2, v2, v5
	v_ashrrev_i32_e32 v3, 31, v2
	v_lshl_add_u64 v[2:3], v[2:3], 2, s[0:1]
	global_load_dword v2, v[2:3], off
	s_waitcnt vmcnt(0)
	v_ashrrev_i32_e32 v32, 1, v2
	v_add_u32_e32 v2, v4, v26
	v_min_i32_e32 v2, v2, v5
	v_ashrrev_i32_e32 v3, 31, v2
	v_lshl_add_u64 v[2:3], v[2:3], 2, s[0:1]
	global_load_dword v2, v[2:3], off
	v_ashrrev_i32_e32 v33, 31, v32
	s_waitcnt vmcnt(0)
	v_ashrrev_i32_e32 v34, 1, v2
	v_add_u32_e32 v2, v4, v78
	v_min_i32_e32 v2, v2, v5
	v_ashrrev_i32_e32 v3, 31, v2
	v_lshl_add_u64 v[2:3], v[2:3], 2, s[0:1]
	global_load_dword v2, v[2:3], off
	v_ashrrev_i32_e32 v35, 31, v34
	s_waitcnt vmcnt(0)
	v_ashrrev_i32_e32 v36, 1, v2
	v_add_u32_e32 v2, v4, v79
	v_min_i32_e32 v2, v2, v5
	v_ashrrev_i32_e32 v3, 31, v2
	v_lshl_add_u64 v[2:3], v[2:3], 2, s[0:1]
	global_load_dword v2, v[2:3], off
	v_ashrrev_i32_e32 v37, 31, v36
	s_waitcnt vmcnt(0)
	v_ashrrev_i32_e32 v38, 1, v2
	v_add_u32_e32 v2, v4, v80
	v_min_i32_e32 v2, v2, v5
	v_ashrrev_i32_e32 v3, 31, v2
	v_lshl_add_u64 v[2:3], v[2:3], 2, s[0:1]
	global_load_dword v2, v[2:3], off
	v_ashrrev_i32_e32 v39, 31, v38
	s_waitcnt vmcnt(0)
	v_ashrrev_i32_e32 v40, 1, v2
	v_add_u32_e32 v2, v4, v81
	v_min_i32_e32 v2, v2, v5
	v_ashrrev_i32_e32 v3, 31, v2
	v_lshl_add_u64 v[2:3], v[2:3], 2, s[0:1]
	global_load_dword v2, v[2:3], off
	v_ashrrev_i32_e32 v41, 31, v40
	s_waitcnt vmcnt(0)
	v_ashrrev_i32_e32 v42, 1, v2
	v_add_u32_e32 v2, v4, v82
	v_min_i32_e32 v2, v2, v5
	v_ashrrev_i32_e32 v3, 31, v2
	v_lshl_add_u64 v[2:3], v[2:3], 2, s[0:1]
	global_load_dword v2, v[2:3], off
	v_ashrrev_i32_e32 v43, 31, v42
	s_waitcnt vmcnt(0)
	v_ashrrev_i32_e32 v44, 1, v2
	v_add_u32_e32 v2, v4, v83
	v_min_i32_e32 v2, v2, v5
	v_ashrrev_i32_e32 v3, 31, v2
	v_lshl_add_u64 v[2:3], v[2:3], 2, s[0:1]
	global_load_dword v2, v[2:3], off
	v_lshlrev_b64 v[4:5], 11, v[34:35]
	v_lshl_add_u64 v[4:5], s[2:3], 0, v[4:5]
	v_lshl_add_u64 v[4:5], v[4:5], 0, v[148:149]
	v_ashrrev_i32_e32 v45, 31, v44
	s_waitcnt vmcnt(0)
; #define TIDX tid_opaque()
; template <class AF, class BF>
; DI void gemm_prologue(AF aptr, BF bptr, int nk, char* smem) {
;   const int tid = TIDX;
; #pragma unroll
;   for (int st = 0; st < 2; st++) {
;     if (st < nk) {
;       char* d = smem + st * 49152 + tid * 16;
; #pragma unroll
;       for (int i = 0; i < 8; i++) glds16(aptr(i) + st * 64, d + i * 4096);
; #pragma unroll
;       for (int i = 0; i < 4; i++) glds16(bptr(i) + st * 64, d + 32768 + i * 4096);
;     }
;   }
; }
; DI void moe_e1_phase(const Params& P, int l, char* smem, int* tb) {
;     ...
;     gemm_prologue([&](int i) { return P.hx + (size_t)tok[i] * D + sc; }, [&](int i) { return ((i & 1) ? w3 : w1) + (size_t)((i >> 1) * 32 + srow) * 1024; }, 16, smem);
	v_ashrrev_i32_e32 v46, 1, v2
	v_mov_b32_e32 v2, v172
	v_ashrrev_i32_e32 v47, 31, v46
	v_lshlrev_b32_e32 v52, 4, v2
	v_lshlrev_b64 v[2:3], 11, v[32:33]
	v_lshl_add_u64 v[2:3], s[2:3], 0, v[2:3]
	v_readfirstlane_b32 s0, v52
	v_add_u32_e32 v6, 0x1000, v52
	v_lshl_add_u64 v[2:3], v[2:3], 0, v[148:149]
	s_mov_b32 m0, s0
	v_readfirstlane_b32 s0, v6
	v_lshlrev_b64 v[6:7], 11, v[36:37]
	v_add_u32_e32 v8, 0x2000, v52
	global_load_lds_dwordx4 v[2:3], off
	s_mov_b32 m0, s0
	v_lshl_add_u64 v[6:7], s[2:3], 0, v[6:7]
	v_readfirstlane_b32 s0, v8
	v_lshlrev_b64 v[8:9], 11, v[38:39]
	v_add_u32_e32 v10, 0x3000, v52
	global_load_lds_dwordx4 v[4:5], off
	v_lshl_add_u64 v[6:7], v[6:7], 0, v[148:149]
	s_mov_b32 m0, s0
	v_lshl_add_u64 v[8:9], s[2:3], 0, v[8:9]
	v_readfirstlane_b32 s0, v10
	v_lshlrev_b64 v[10:11], 11, v[40:41]
	v_add_u32_e32 v12, 0x4000, v52
	global_load_lds_dwordx4 v[6:7], off
	v_lshl_add_u64 v[8:9], v[8:9], 0, v[148:149]
	s_mov_b32 m0, s0
	v_lshl_add_u64 v[10:11], s[2:3], 0, v[10:11]
	v_readfirstlane_b32 s0, v12
	v_lshlrev_b64 v[12:13], 11, v[42:43]
	v_add_u32_e32 v14, 0x5000, v52
	global_load_lds_dwordx4 v[8:9], off
	v_lshl_add_u64 v[10:11], v[10:11], 0, v[148:149]
	s_mov_b32 m0, s0
	v_lshl_add_u64 v[12:13], s[2:3], 0, v[12:13]
	v_readfirstlane_b32 s0, v14
	v_lshlrev_b64 v[14:15], 11, v[44:45]
	v_add_u32_e32 v16, 0x6000, v52
	global_load_lds_dwordx4 v[10:11], off
	v_lshl_add_u64 v[12:13], v[12:13], 0, v[148:149]
	s_mov_b32 m0, s0
	v_lshl_add_u64 v[14:15], s[2:3], 0, v[14:15]
	v_readfirstlane_b32 s0, v16
	v_lshlrev_b64 v[16:17], 11, v[46:47]
	v_add_u32_e32 v18, 0x7000, v52
	global_load_lds_dwordx4 v[12:13], off
	v_lshl_add_u64 v[14:15], v[14:15], 0, v[148:149]
	s_mov_b32 m0, s0
	v_lshl_add_u64 v[16:17], s[2:3], 0, v[16:17]
	v_readfirstlane_b32 s0, v18
	v_add_u32_e32 v20, 0x8000, v52
	global_load_lds_dwordx4 v[14:15], off
	v_lshl_add_u64 v[16:17], v[16:17], 0, v[148:149]
	s_mov_b32 m0, s0
	v_readfirstlane_b32 s0, v20
	v_add_u32_e32 v22, 0x9000, v52
	global_load_lds_dwordx4 v[16:17], off
	v_lshl_add_u64 v[18:19], v[28:29], 0, v[48:49]
	s_mov_b32 m0, s0
	v_readfirstlane_b32 s0, v22
	v_add_u32_e32 v25, 0xa000, v52
	global_load_lds_dwordx4 v[18:19], off
	v_lshl_add_u64 v[20:21], v[30:31], 0, v[48:49]
	s_mov_b32 m0, s0
	v_readfirstlane_b32 s0, v25
	v_add_u32_e32 v25, 0xb000, v52
	global_load_lds_dwordx4 v[20:21], off
	v_lshl_add_u64 v[22:23], v[28:29], 0, v[50:51]
	s_mov_b32 m0, s0
	v_readfirstlane_b32 s0, v25
	v_add_u32_e32 v25, 0xc000, v52
	global_load_lds_dwordx4 v[22:23], off
	s_mov_b32 m0, s0
	v_readfirstlane_b32 s0, v25
	global_load_lds_dwordx4 v[56:57], off
	v_lshl_add_u64 v[2:3], v[2:3], 0, s[92:93]
	s_mov_b32 m0, s0
	s_nop 0
	global_load_lds_dwordx4 v[2:3], off
	v_lshl_add_u64 v[2:3], v[4:5], 0, s[92:93]
	v_add_u32_e32 v4, 0xd000, v52
	s_nop 0
	v_readfirstlane_b32 s0, v4
	v_add_u32_e32 v4, 0xe000, v52
	s_mov_b32 m0, s0
	v_readfirstlane_b32 s0, v4
	v_add_u32_e32 v4, 0xf000, v52
	global_load_lds_dwordx4 v[2:3], off
	v_lshl_add_u64 v[2:3], v[6:7], 0, s[92:93]
	s_mov_b32 m0, s0
	v_readfirstlane_b32 s0, v4
	v_add_u32_e32 v4, 0x10000, v52
	global_load_lds_dwordx4 v[2:3], off
	v_lshl_add_u64 v[2:3], v[8:9], 0, s[92:93]
	s_mov_b32 m0, s0
	v_readfirstlane_b32 s0, v4
	v_add_u32_e32 v4, 0x11000, v52
	global_load_lds_dwordx4 v[2:3], off
	v_lshl_add_u64 v[2:3], v[10:11], 0, s[92:93]
	s_mov_b32 m0, s0
	v_readfirstlane_b32 s0, v4
	v_add_u32_e32 v4, 0x12000, v52
	global_load_lds_dwordx4 v[2:3], off
	v_lshl_add_u64 v[2:3], v[12:13], 0, s[92:93]
	s_mov_b32 m0, s0
	v_readfirstlane_b32 s0, v4
	v_add_u32_e32 v4, 0x13000, v52
	global_load_lds_dwordx4 v[2:3], off
	v_lshl_add_u64 v[2:3], v[14:15], 0, s[92:93]
	s_mov_b32 m0, s0
	v_readfirstlane_b32 s0, v4
	v_add_u32_e32 v4, 0x14000, v52
	global_load_lds_dwordx4 v[2:3], off
	v_lshl_add_u64 v[2:3], v[16:17], 0, s[92:93]
	s_mov_b32 m0, s0
	v_readfirstlane_b32 s0, v4
	v_add_u32_e32 v4, 0x15000, v52
	global_load_lds_dwordx4 v[2:3], off
	v_lshl_add_u64 v[2:3], v[18:19], 0, s[92:93]
	s_mov_b32 m0, s0
	v_readfirstlane_b32 s0, v4
	v_add_u32_e32 v4, 0x16000, v52
	global_load_lds_dwordx4 v[2:3], off
	v_lshl_add_u64 v[2:3], v[20:21], 0, s[92:93]
	s_mov_b32 m0, s0
	v_readfirstlane_b32 s0, v4
	v_add_u32_e32 v4, 0x17000, v52
	global_load_lds_dwordx4 v[2:3], off
	v_lshl_add_u64 v[2:3], v[22:23], 0, s[92:93]
	s_mov_b32 m0, s0
	v_readfirstlane_b32 s0, v4
	global_load_lds_dwordx4 v[2:3], off
	v_lshl_add_u64 v[2:3], v[56:57], 0, s[92:93]
	s_mov_b32 m0, s0
	v_readlane_b32 s0, v254, 32
	global_load_lds_dwordx4 v[2:3], off
	v_lshl_add_u64 v[52:53], s[2:3], 0, v[148:149]
	v_lshlrev_b32_e32 v148, 4, v1
	v_readlane_b32 s1, v254, 33
	v_lshlrev_b32_e32 v56, 1, v0
	s_nop 0
	v_lshl_add_u64 v[54:55], s[0:1], 0, v[148:149]
	s_branch .LBB0_569

; DI void moe_e1_phase(const Params& P, int l, char* smem, int* tb) {
;     ...
;   auto setup = [&](int rt, int nt, int (&tok)[8], const half_t*& w1, const half_t*& w3) {
;     int e = 0;
;     while (tb[e + 1] <= rt) e++;
;     const int rl = rt - tb[e], cnt = P.cnt[l * 32 + e];
;     const int* lst = P.list + (size_t)e * LCAP;
;     w1 = P.Wt1 + ((size_t)(l * 32 + e) * 512 + nt * 64) * 1024 + sc;
;     w3 = P.Wt3 + ((size_t)(l * 32 + e) * 512 + nt * 64) * 1024 + sc;
; #pragma unroll
;     for (int i = 0; i < 8; i++) tok[i] = lst[min(rl * 256 + i * 32 + srow, cnt - 1)] >> 1;
;   };
.LBB0_573:
	v_cndmask_b32_e64 v5, 0, 1, s[6:7]
	v_cmp_ne_u32_e64 s[2:3], 1, v5
	s_andn2_b64 vcc, exec, s[6:7]
	s_cbranch_vccnz .LBB0_577
	v_and_b32_e32 v5, 31, v172
	v_lshlrev_b32_e32 v5, 2, v5
	v_add_u32_e32 v5, 0x26004, v5
	ds_read_b32 v5, v5
	s_waitcnt lgkmcnt(0)
	v_cmp_ge_i32_e32 vcc, s21, v5
	s_bcnt1_i32_b32 s5, vcc_lo
	s_lshl_b32 s6, s5, 2
	s_add_i32 s6, s6, 0x26000
.LBB0_575:
	s_add_i32 s84, s5, s23
	s_lshl_b64 s[8:9], s[84:85], 2
	v_readlane_b32 s34, v253, 63
	v_readlane_b32 s35, v255, 0
	s_add_u32 s8, s34, s8
	s_addc_u32 s9, s35, s9
	s_lshl_b32 s8, s5, 2
	s_add_i32 s8, s8, 0x24000
	v_mov_b32_e32 v5, s8
	ds_read_b32 v5, v5
	v_mov_b32_e32 v7, s6
	ds_read_b32 v7, v7
	s_mul_hi_u32 s7, s5, 0x84000
	s_mul_i32 s5, s5, 0x84000
	v_readlane_b32 s8, v255, 24
	v_readlane_b32 s9, v255, 25
	s_waitcnt lgkmcnt(0)
	v_sub_u32_e32 v7, s21, v7
	v_lshlrev_b32_e32 v7, 8, v7
	v_add_u32_e32 v9, v7, v24
	s_add_u32 s6, s8, s5
	v_add_u32_e32 v11, v7, v26
	v_add_u32_e32 v13, v7, v78
	v_add_u32_e32 v15, v7, v79
	v_add_u32_e32 v17, v7, v80
	v_add_u32_e32 v19, v7, v81
	v_add_u32_e32 v21, v7, v82
	v_add_u32_e32 v7, v7, v83
	s_addc_u32 s7, s9, s7
	s_lshl_b64 s[8:9], s[84:85], 20
	v_readlane_b32 s5, v253, 53
	v_readlane_b32 s29, v253, 54
	v_mov_b32_e32 v57, v149
	s_waitcnt lgkmcnt(0)
	v_add_u32_e32 v5, -1, v5
	v_min_i32_e32 v20, v9, v5
	v_min_i32_e32 v22, v11, v5
	v_min_i32_e32 v28, v13, v5
	v_min_i32_e32 v30, v15, v5
	v_min_i32_e32 v32, v17, v5
	v_min_i32_e32 v34, v19, v5
	v_min_i32_e32 v36, v21, v5
	v_min_i32_e32 v38, v7, v5
	v_ashrrev_i32_e32 v21, 31, v20
	v_ashrrev_i32_e32 v23, 31, v22
	v_ashrrev_i32_e32 v29, 31, v28
	v_ashrrev_i32_e32 v31, 31, v30
	v_ashrrev_i32_e32 v33, 31, v32
	v_ashrrev_i32_e32 v35, 31, v34
	v_ashrrev_i32_e32 v37, 31, v36
	v_ashrrev_i32_e32 v39, 31, v38
	v_lshl_add_u64 v[20:21], v[20:21], 2, s[6:7]
	v_lshl_add_u64 v[22:23], v[22:23], 2, s[6:7]
	v_lshl_add_u64 v[28:29], v[28:29], 2, s[6:7]
	v_lshl_add_u64 v[30:31], v[30:31], 2, s[6:7]
	v_lshl_add_u64 v[32:33], v[32:33], 2, s[6:7]
	v_lshl_add_u64 v[34:35], v[34:35], 2, s[6:7]
	v_lshl_add_u64 v[36:37], v[36:37], 2, s[6:7]
	v_lshl_add_u64 v[38:39], v[38:39], 2, s[6:7]
	global_load_dword v5, v[20:21], off
	global_load_dword v7, v[22:23], off
	global_load_dword v9, v[28:29], off
	global_load_dword v11, v[30:31], off
	global_load_dword v13, v[32:33], off
	global_load_dword v15, v[34:35], off
	global_load_dword v17, v[36:37], off
	global_load_dword v19, v[38:39], off
	s_lshl_b32 s6, s22, 6
	s_ashr_i32 s7, s6, 31
	s_add_u32 s5, s5, s8
	s_addc_u32 s29, s29, s9
	s_lshl_b64 s[6:7], s[6:7], 11
	s_add_u32 s34, s5, s6
	s_addc_u32 s35, s29, s7
	v_readlane_b32 s5, v253, 55
	s_add_u32 s5, s5, s8
	v_readlane_b32 s8, v253, 56
	s_addc_u32 s8, s8, s9
	s_add_u32 s6, s5, s6
	s_addc_u32 s7, s8, s7
	v_lshl_add_u64 v[28:29], s[34:35], 0, v[56:57]
	v_lshl_add_u64 v[30:31], s[6:7], 0, v[56:57]
	s_waitcnt vmcnt(7)
	v_ashrrev_i32_e32 v32, 1, v5
	s_waitcnt vmcnt(6)
	v_ashrrev_i32_e32 v34, 1, v7
	s_waitcnt vmcnt(5)
	v_ashrrev_i32_e32 v36, 1, v9
	s_waitcnt vmcnt(4)
	v_ashrrev_i32_e32 v38, 1, v11
	s_waitcnt vmcnt(3)
	v_ashrrev_i32_e32 v40, 1, v13
	s_waitcnt vmcnt(2)
	v_ashrrev_i32_e32 v42, 1, v15
	s_waitcnt vmcnt(1)
	v_ashrrev_i32_e32 v44, 1, v17
	s_waitcnt vmcnt(0)
	v_ashrrev_i32_e32 v46, 1, v19
	s_branch .LBB0_578

; DI void moe_e2_phase(const Params& P, int l, char* smem, int* tb) {
;     ...
;   auto ptrs = [&](int rt, int nt, const half_t*& a0, const half_t*& b0) {
;     int e = 0;
;     while (tb[e + 1] <= rt) e++;
;     a0 = P.H + ((size_t)rt * 256 + srow) * 512 + sc;
;     b0 = P.Wt2 + ((size_t)(l * 32 + e) * 1024 + nt * 128 + srow) * 512 + sc;
;   };
;   int it = 0, rt, nt;
;   bool have = next_tile(it, MT, 8, rt, nt);
;   const half_t* a0 = nullptr; const half_t* b0 = nullptr;
;   if (have) {
;     asm volatile("" : "+s"(rt), "+s"(nt));
;     ptrs(rt, nt, a0, b0);
;     gemm_prologue([&](int i) { return a0 + (size_t)i * 32 * 512; }, [&](int i) { return b0 + (size_t)i * 32 * 512; }, 8, smem);
.LBB0_603:
	s_and_b32 s1, s3, 0x7ffffff8
	s_add_i32 s1, s1, s78
	s_cmp_lt_i32 s2, s9
	s_cselect_b64 s[4:5], -1, 0
	s_mov_b32 s0, s7
	s_mov_b32 s11, s6
	s_and_b64 s[6:7], s[4:5], exec
	s_cselect_b32 s7, s1, s0
	s_cselect_b32 s6, s36, s11
	s_cmp_ge_i32 s7, s8
	s_cselect_b64 s[20:21], -1, 0
	s_and_b64 s[20:21], s[4:5], s[20:21]
	s_add_i32 s10, s10, 1
	s_add_i32 s3, s3, 32
	s_add_i32 s2, s2, 8
	s_and_b64 vcc, exec, s[20:21]
	s_cbranch_vccnz .LBB0_603
	v_lshrrev_b32_e32 v1, 4, v0
	v_xor_b32_e32 v0, v1, v0
	v_lshlrev_b32_e32 v0, 3, v0
	v_cndmask_b32_e64 v1, 0, 1, s[4:5]
	v_and_b32_e32 v0, 56, v0
	v_ashrrev_i32_e32 v24, 3, v16
	v_mov_b64_e32 v[28:29], 0
	v_cmp_ne_u32_e64 s[2:3], 1, v1
	s_andn2_b64 vcc, exec, s[4:5]
	v_mov_b64_e32 v[26:27], 0
	s_cbranch_vccnz .LBB0_608
	s_mov_b32 s11, s36
	s_mov_b32 s0, s1
	v_and_b32_e32 v1, 31, v172
	v_lshlrev_b32_e32 v1, 2, v1
	v_add_u32_e32 v1, 0x26004, v1
	ds_read_b32 v1, v1
	s_waitcnt lgkmcnt(0)
	v_cmp_ge_i32_e32 vcc, s0, v1
	s_bcnt1_i32_b32 s4, vcc_lo
	s_lshl_b32 s1, s4, 2
	s_add_i32 s1, s1, 0x26008
.LBB0_606:
	s_ashr_i32 s1, s0, 31
	s_lshl_b64 s[6:7], s[0:1], 18
	v_readlane_b32 s20, v255, 62
	v_readlane_b32 s21, v255, 63
	s_add_u32 s6, s20, s6
	v_ashrrev_i32_e32 v25, 31, v24
	s_addc_u32 s7, s21, s7
	s_lshl_b32 s1, s22, 5
	v_lshlrev_b64 v[2:3], 10, v[24:25]
	s_add_i32 s84, s4, s1
	s_lshl_b32 s4, s11, 7
	v_lshl_add_u64 v[2:3], s[6:7], 0, v[2:3]
	v_lshlrev_b32_e32 v148, 1, v0
	s_ashr_i32 s5, s4, 31
	v_mov_b32_e32 v1, v172
	v_lshl_add_u64 v[26:27], v[2:3], 0, v[148:149]
	v_lshl_add_u64 v[2:3], s[4:5], 0, v[24:25]
	s_lshl_b64 s[4:5], s[84:85], 20
	v_readlane_b32 s1, v253, 57
	s_add_u32 s4, s1, s4
	v_readlane_b32 s1, v253, 58
	v_lshlrev_b32_e32 v1, 4, v1
	v_lshlrev_b64 v[2:3], 10, v[2:3]
	s_addc_u32 s5, s1, s5
	v_readfirstlane_b32 s1, v1
	v_add_u32_e32 v4, 0x1000, v1
	v_lshl_add_u64 v[2:3], s[4:5], 0, v[2:3]
	s_mov_b32 m0, s1
	s_mov_b64 s[6:7], 0x8000
	v_readfirstlane_b32 s1, v4
	v_add_u32_e32 v4, 0x2000, v1
	v_lshl_add_u64 v[28:29], v[2:3], 0, v[148:149]
	global_load_lds_dwordx4 v[26:27], off
	v_lshl_add_u64 v[2:3], v[26:27], 0, s[6:7]
	s_mov_b32 m0, s1
	v_readfirstlane_b32 s1, v4
	v_add_u32_e32 v4, 0x3000, v1
	global_load_lds_dwordx4 v[2:3], off
	v_lshl_add_u64 v[2:3], v[26:27], 0, s[68:69]
	s_mov_b32 m0, s1
	s_mov_b64 s[20:21], 0x18000
	v_readfirstlane_b32 s1, v4
	v_add_u32_e32 v4, 0x4000, v1
	global_load_lds_dwordx4 v[2:3], off
	v_lshl_add_u64 v[2:3], v[26:27], 0, s[20:21]
	s_mov_b32 m0, s1
	s_mov_b64 s[4:5], 0x20000
	v_readfirstlane_b32 s1, v4
	v_add_u32_e32 v4, 0x5000, v1
	global_load_lds_dwordx4 v[2:3], off
	v_lshl_add_u64 v[2:3], v[26:27], 0, s[4:5]
	s_mov_b32 m0, s1
	s_mov_b64 s[4:5], 0x28000
	v_readfirstlane_b32 s1, v4
	v_add_u32_e32 v4, 0x6000, v1
	global_load_lds_dwordx4 v[2:3], off
	v_lshl_add_u64 v[2:3], v[26:27], 0, s[4:5]
	s_mov_b32 m0, s1
	s_mov_b64 s[4:5], 0x30000
	v_readfirstlane_b32 s1, v4
	v_add_u32_e32 v4, 0x7000, v1
	global_load_lds_dwordx4 v[2:3], off
	v_lshl_add_u64 v[2:3], v[26:27], 0, s[4:5]
	s_mov_b32 m0, s1
	s_mov_b64 s[4:5], 0x38000
	v_readfirstlane_b32 s1, v4
	global_load_lds_dwordx4 v[2:3], off
	v_lshl_add_u64 v[2:3], v[26:27], 0, s[4:5]
	s_mov_b32 m0, s1
	v_add_u32_e32 v4, 0x9000, v1
	global_load_lds_dwordx4 v[2:3], off
	v_add_u32_e32 v2, 0x8000, v1
	s_mov_b64 s[4:5], 0x10080
	v_readfirstlane_b32 s1, v2
	s_mov_b32 m0, s1
	v_readfirstlane_b32 s1, v4
	v_add_u32_e32 v4, 0xa000, v1
	global_load_lds_dwordx4 v[28:29], off
	v_lshl_add_u64 v[2:3], v[28:29], 0, s[6:7]
	s_mov_b32 m0, s1
	v_readfirstlane_b32 s1, v4
	v_add_u32_e32 v4, 0xb000, v1
	global_load_lds_dwordx4 v[2:3], off
	v_lshl_add_u64 v[2:3], v[28:29], 0, s[68:69]
	s_mov_b32 m0, s1
	v_readfirstlane_b32 s1, v4
	v_add_u32_e32 v4, 0xc000, v1
	global_load_lds_dwordx4 v[2:3], off
	v_lshl_add_u64 v[2:3], v[28:29], 0, s[20:21]
	s_mov_b32 m0, s1
	v_readfirstlane_b32 s1, v4
	v_add_u32_e32 v4, 0xd000, v1
	global_load_lds_dwordx4 v[2:3], off
	v_lshl_add_u64 v[2:3], v[26:27], 0, s[92:93]
	s_mov_b32 m0, s1
	s_mov_b64 s[20:21], 0x8080
	v_readfirstlane_b32 s1, v4
	v_add_u32_e32 v4, 0xe000, v1
	global_load_lds_dwordx4 v[2:3], off
	v_lshl_add_u64 v[2:3], v[26:27], 0, s[20:21]
	s_mov_b32 m0, s1
	v_readfirstlane_b32 s1, v4
	v_add_u32_e32 v4, 0xf000, v1
	global_load_lds_dwordx4 v[2:3], off
	v_lshl_add_u64 v[2:3], v[26:27], 0, s[4:5]
	s_mov_b32 m0, s1
	s_mov_b64 s[22:23], 0x18080
	v_readfirstlane_b32 s1, v4
	v_add_u32_e32 v4, 0x10000, v1
	global_load_lds_dwordx4 v[2:3], off
	v_lshl_add_u64 v[2:3], v[26:27], 0, s[22:23]
	s_mov_b32 m0, s1
	s_mov_b64 s[6:7], 0x20080
	v_readfirstlane_b32 s1, v4
	v_add_u32_e32 v4, 0x11000, v1
	global_load_lds_dwordx4 v[2:3], off
	v_lshl_add_u64 v[2:3], v[26:27], 0, s[6:7]
	s_mov_b32 m0, s1
	s_mov_b64 s[6:7], 0x28080
	v_readfirstlane_b32 s1, v4
	v_add_u32_e32 v4, 0x12000, v1
	global_load_lds_dwordx4 v[2:3], off
	v_lshl_add_u64 v[2:3], v[26:27], 0, s[6:7]
	s_mov_b32 m0, s1
	s_mov_b64 s[6:7], 0x30080
	v_readfirstlane_b32 s1, v4
	v_add_u32_e32 v4, 0x13000, v1
	global_load_lds_dwordx4 v[2:3], off
	v_lshl_add_u64 v[2:3], v[26:27], 0, s[6:7]
	s_mov_b32 m0, s1
	s_mov_b64 s[6:7], 0x38080
	v_readfirstlane_b32 s1, v4
	v_add_u32_e32 v4, 0x14000, v1
	global_load_lds_dwordx4 v[2:3], off
	v_lshl_add_u64 v[2:3], v[26:27], 0, s[6:7]
	s_mov_b32 m0, s1
	v_readfirstlane_b32 s1, v4
	v_add_u32_e32 v4, 0x15000, v1
	global_load_lds_dwordx4 v[2:3], off
	v_lshl_add_u64 v[2:3], v[28:29], 0, s[92:93]
	s_mov_b32 m0, s1
	v_readfirstlane_b32 s1, v4
	v_add_u32_e32 v4, 0x16000, v1
	global_load_lds_dwordx4 v[2:3], off
	v_lshl_add_u64 v[2:3], v[28:29], 0, s[20:21]
	s_mov_b32 m0, s1
	v_readfirstlane_b32 s1, v4
	v_add_u32_e32 v1, 0x17000, v1
	global_load_lds_dwordx4 v[2:3], off
	v_lshl_add_u64 v[2:3], v[28:29], 0, s[4:5]
	s_mov_b32 m0, s1
	v_readfirstlane_b32 s1, v1
	global_load_lds_dwordx4 v[2:3], off
	v_lshl_add_u64 v[2:3], v[28:29], 0, s[22:23]
	s_mov_b32 m0, s1
	v_readlane_b32 s22, v255, 26
	global_load_lds_dwordx4 v[2:3], off
	v_readlane_b32 s23, v255, 27

; #define TIDX tid_opaque()
; DI void moe_e2_phase(const Params& P, int l, char* smem, int* tb) {
;     ...
;     const int tid2 = TIDX, lane2 = tid2 & 63, wave2 = tid2 >> 6, wr2 = wave2 >> 1, wc2 = wave2 & 1;
;     int e = 0;
;     while (tb[e + 1] <= rt) e++;
;     const int rl = rt - tb[e], cnt = P.cnt[l * 32 + e];
;     const int* lst = P.list + (size_t)e * LCAP; const float* lstw = P.listW + (size_t)e * LCAP;
;     int aa[2][8]; float ww[2][8];
; #pragma unroll
;     for (int h = 0; h < 2; h++)
; #pragma unroll
;       for (int i = 0; i < 8; i++) {
;         const int idx = rl * 256 + wr2 * 128 + h * 64 + ((i * 64 + lane2) >> 3);
;         const int ic = min(idx, cnt - 1);
;         const int av = lst[ic]; const float wv = lstw[ic];
;         aa[h][i] = idx < cnt ? av : -1; ww[h][i] = wv;
;       }
;     f4 acc[8][4];
.LBB0_611:
	s_mov_b32 s6, s11
	v_mov_b32_e32 v87, v172
	v_and_b32_e32 v0, 31, v172
	v_lshlrev_b32_e32 v0, 2, v0
	v_add_u32_e32 v0, 0x26004, v0
	ds_read_b32 v0, v0
	s_waitcnt lgkmcnt(0)
	v_cmp_ge_i32_e32 vcc, s0, v0
	s_bcnt1_i32_b32 s1, vcc_lo
	s_lshl_b32 s2, s1, 2
	s_add_i32 s2, s2, 0x26000
.LBB0_612:
	s_add_i32 s84, s1, s20
	v_mov_b32_e32 v0, s2
	s_lshl_b64 s[2:3], s[84:85], 2
	v_readlane_b32 s4, v253, 63
	v_readlane_b32 s5, v255, 0
	s_add_u32 s2, s4, s2
	s_addc_u32 s3, s5, s3
	s_lshl_b32 s2, s1, 2
	s_add_i32 s2, s2, 0x24000
	v_mov_b32_e32 v33, s2
	ds_read_b32 v33, v33
	ds_read_b32 v0, v0
	v_and_b32_e32 v1, 0xffffff80, v87
	s_mul_hi_u32 s3, s1, 0x84000
	s_mul_i32 s1, s1, 0x84000
	v_readlane_b32 s4, v255, 24
	s_waitcnt lgkmcnt(0)
	v_sub_u32_e32 v0, s0, v0
	v_lshl_add_u32 v1, v0, 8, v1
	v_bfe_u32 v86, v87, 3, 3
	v_readlane_b32 s5, v255, 25
	s_add_u32 s4, s4, s1
	v_or_b32_e32 v88, v1, v86
	s_addc_u32 s5, s5, s3
	v_readlane_b32 s22, v254, 0
	v_readlane_b32 s23, v254, 1
	s_add_u32 s2, s22, s1
	s_addc_u32 s3, s23, s3
	v_or_b32_e32 v83, 8, v86
	v_or_b32_e32 v84, v1, v83
	v_or_b32_e32 v80, 16, v86
	v_or_b32_e32 v81, v1, v80
	v_or_b32_e32 v77, 24, v86
	v_or_b32_e32 v78, v1, v77
	v_or_b32_e32 v74, 32, v86
	v_or_b32_e32 v75, v1, v74
	v_or_b32_e32 v69, 40, v86
	v_or_b32_e32 v70, v1, v69
	v_or_b32_e32 v66, 48, v86
	v_or_b32_e32 v67, v1, v66
	v_or_b32_e32 v63, 56, v86
	v_or_b32_e32 v64, v1, v63
	v_or_b32_e32 v1, 64, v1
	v_or_b32_e32 v72, v1, v86
	v_or_b32_e32 v59, v1, v83
	v_or_b32_e32 v55, v1, v80
	v_or_b32_e32 v51, v1, v77
	v_or_b32_e32 v47, v1, v74
	v_or_b32_e32 v43, v1, v69
	v_or_b32_e32 v39, v1, v66
	v_or_b32_e32 v35, v1, v63
	s_mov_b32 s1, 0x8040
	v_accvgpr_write_b32 a3, 0
	v_accvgpr_write_b32 a2, 0
	v_accvgpr_write_b32 a1, 0
	v_accvgpr_write_b32 a0, 0
	v_accvgpr_write_b32 a7, 0
	v_accvgpr_write_b32 a6, 0
	v_accvgpr_write_b32 a5, 0
	v_accvgpr_write_b32 a4, 0
	v_accvgpr_write_b32 a11, 0
	v_accvgpr_write_b32 a10, 0
	v_accvgpr_write_b32 a9, 0
	v_accvgpr_write_b32 a8, 0
	v_accvgpr_write_b32 a19, 0
	v_accvgpr_write_b32 a18, 0
	v_accvgpr_write_b32 a17, 0
	v_accvgpr_write_b32 a16, 0
	v_accvgpr_write_b32 a35, 0
	v_accvgpr_write_b32 a34, 0
	v_accvgpr_write_b32 a33, 0
	v_accvgpr_write_b32 a32, 0
	v_accvgpr_write_b32 a51, 0
	v_accvgpr_write_b32 a50, 0
	v_accvgpr_write_b32 a49, 0
	v_accvgpr_write_b32 a48, 0
	v_accvgpr_write_b32 a67, 0
	v_accvgpr_write_b32 a66, 0
	v_accvgpr_write_b32 a65, 0
	v_accvgpr_write_b32 a64, 0
	v_accvgpr_write_b32 a83, 0
	v_accvgpr_write_b32 a82, 0
	v_accvgpr_write_b32 a81, 0
	v_accvgpr_write_b32 a80, 0
	v_accvgpr_write_b32 a99, 0
	v_accvgpr_write_b32 a98, 0
	v_accvgpr_write_b32 a97, 0
	v_accvgpr_write_b32 a96, 0
	v_accvgpr_write_b32 a115, 0
	v_accvgpr_write_b32 a114, 0
	v_accvgpr_write_b32 a113, 0
	s_waitcnt lgkmcnt(0)
	v_add_u32_e32 v0, -1, v33
	v_min_i32_e32 v2, v88, v0
	v_ashrrev_i32_e32 v3, 31, v2
	v_lshlrev_b64 v[2:3], 2, v[2:3]
	v_lshl_add_u64 v[4:5], s[4:5], 0, v[2:3]
	v_lshl_add_u64 v[2:3], s[2:3], 0, v[2:3]
	global_load_dword v89, v[4:5], off
	global_load_dword v62, v[2:3], off
	v_min_i32_e32 v2, v84, v0
	v_ashrrev_i32_e32 v3, 31, v2
	v_lshlrev_b64 v[2:3], 2, v[2:3]
	v_lshl_add_u64 v[4:5], s[4:5], 0, v[2:3]
	v_lshl_add_u64 v[2:3], s[2:3], 0, v[2:3]
	global_load_dword v85, v[4:5], off
	global_load_dword v60, v[2:3], off
	v_min_i32_e32 v2, v81, v0
	v_ashrrev_i32_e32 v3, 31, v2
	v_lshlrev_b64 v[2:3], 2, v[2:3]
	v_lshl_add_u64 v[4:5], s[4:5], 0, v[2:3]
	v_lshl_add_u64 v[2:3], s[2:3], 0, v[2:3]
	global_load_dword v82, v[4:5], off
	global_load_dword v58, v[2:3], off
	v_min_i32_e32 v2, v78, v0
	v_ashrrev_i32_e32 v3, 31, v2
	v_lshlrev_b64 v[2:3], 2, v[2:3]
	v_lshl_add_u64 v[4:5], s[4:5], 0, v[2:3]
	v_lshl_add_u64 v[2:3], s[2:3], 0, v[2:3]
	global_load_dword v79, v[4:5], off
	global_load_dword v56, v[2:3], off
	v_min_i32_e32 v2, v75, v0
	v_ashrrev_i32_e32 v3, 31, v2
	v_lshlrev_b64 v[2:3], 2, v[2:3]
	v_lshl_add_u64 v[4:5], s[4:5], 0, v[2:3]
	v_lshl_add_u64 v[2:3], s[2:3], 0, v[2:3]
	global_load_dword v76, v[4:5], off
	global_load_dword v54, v[2:3], off
	v_min_i32_e32 v2, v70, v0
	v_ashrrev_i32_e32 v3, 31, v2
	v_lshlrev_b64 v[2:3], 2, v[2:3]
	v_lshl_add_u64 v[4:5], s[4:5], 0, v[2:3]
	v_lshl_add_u64 v[2:3], s[2:3], 0, v[2:3]
	global_load_dword v71, v[4:5], off
	global_load_dword v52, v[2:3], off
	v_min_i32_e32 v2, v67, v0
	v_ashrrev_i32_e32 v3, 31, v2
	v_lshlrev_b64 v[2:3], 2, v[2:3]
	v_lshl_add_u64 v[4:5], s[4:5], 0, v[2:3]
	v_lshl_add_u64 v[2:3], s[2:3], 0, v[2:3]
	global_load_dword v68, v[4:5], off
	global_load_dword v50, v[2:3], off
	v_min_i32_e32 v2, v64, v0
	v_ashrrev_i32_e32 v3, 31, v2
	v_lshlrev_b64 v[2:3], 2, v[2:3]
	v_lshl_add_u64 v[4:5], s[4:5], 0, v[2:3]
	v_lshl_add_u64 v[2:3], s[2:3], 0, v[2:3]
	global_load_dword v65, v[4:5], off
	global_load_dword v48, v[2:3], off
	v_min_i32_e32 v2, v72, v0
	v_ashrrev_i32_e32 v3, 31, v2
	v_lshlrev_b64 v[2:3], 2, v[2:3]
	v_lshl_add_u64 v[4:5], s[4:5], 0, v[2:3]
	v_lshl_add_u64 v[2:3], s[2:3], 0, v[2:3]
	global_load_dword v73, v[4:5], off
	global_load_dword v46, v[2:3], off
	v_min_i32_e32 v2, v59, v0
	v_ashrrev_i32_e32 v3, 31, v2
	v_lshlrev_b64 v[2:3], 2, v[2:3]
	v_lshl_add_u64 v[4:5], s[4:5], 0, v[2:3]
	v_lshl_add_u64 v[2:3], s[2:3], 0, v[2:3]
	global_load_dword v61, v[4:5], off
	global_load_dword v44, v[2:3], off
	v_min_i32_e32 v2, v55, v0
	v_ashrrev_i32_e32 v3, 31, v2
	v_lshlrev_b64 v[2:3], 2, v[2:3]
	v_lshl_add_u64 v[4:5], s[4:5], 0, v[2:3]
	v_lshl_add_u64 v[2:3], s[2:3], 0, v[2:3]
	global_load_dword v57, v[4:5], off
	global_load_dword v42, v[2:3], off
	v_min_i32_e32 v2, v51, v0
; DI void wait_vm0() { asm volatile("s_waitcnt vmcnt(0)" ::: "memory"); }
; DI h8 lds128(unsigned a) { h8 r; asm volatile("ds_read_b128 %0, %1" : "=v"(r) : "v"(a)); return r; }
; DI void raw_barrier() { asm volatile("" ::: "memory"); __builtin_amdgcn_s_barrier(); asm volatile("" ::: "memory"); }
; template <bool PRE = false, class AF, class BF>
; DI void gemm256(AF aptr, BF bptr, int nk, char* smem, f4 (&acc)[8][4]) {
;     ...
;   for (int kt = 0; kt < nk; kt++) {
;     if (kt + 1 < nk) asm volatile("s_waitcnt vmcnt(12)" ::: "memory"); else wait_vm0();
;     raw_barrier();
;     if (kt + 2 < nk) issue(kt + 2, st == 0 ? 2 : st - 1);
;     const unsigned base = sbase + st * 49152;
;     st = st == 2 ? 0 : st + 1;
;     h8 a0[8], b0[4], a1[8], b1[4];
; #pragma unroll
;     for (int m = 0; m < 8; m++) a0[m] = lds128(base + offA + m * 2048);
; #pragma unroll
;     for (int n = 0; n < 4; n++) b0[n] = lds128(base + offB + n * 2048);
; #pragma unroll
;     for (int m = 0; m < 8; m++) a1[m] = lds128(base + (offA ^ 64) + m * 2048);
; #pragma unroll
;     for (int n = 0; n < 4; n++) b1[n] = lds128(base + (offB ^ 64) + n * 2048);
; DI void moe_e2_phase(const Params& P, int l, char* smem, int* tb) {
;     ...
;     for (int h = 0; h < 2; h++)
; #pragma unroll
;       for (int i = 0; i < 8; i++) {
;         const int idx = rl * 256 + wr2 * 128 + h * 64 + ((i * 64 + lane2) >> 3);
;         const int ic = min(idx, cnt - 1);
;         const int av = lst[ic]; const float wv = lstw[ic];
;         aa[h][i] = idx < cnt ? av : -1; ww[h][i] = wv;
;       }
;     f4 acc[8][4];
;     gemm256<true>([&](int i) { return a0 + (size_t)i * 32 * 512; }, [&](int i) { return b0 + (size_t)i * 32 * 512; }, 8, smem, acc);
	v_ashrrev_i32_e32 v3, 31, v2
	v_lshlrev_b64 v[2:3], 2, v[2:3]
	v_lshl_add_u64 v[4:5], s[4:5], 0, v[2:3]
	v_lshl_add_u64 v[2:3], s[2:3], 0, v[2:3]
	global_load_dword v53, v[4:5], off
	global_load_dword v40, v[2:3], off
	v_min_i32_e32 v2, v47, v0
	v_ashrrev_i32_e32 v3, 31, v2
	v_lshlrev_b64 v[2:3], 2, v[2:3]
	v_lshl_add_u64 v[4:5], s[4:5], 0, v[2:3]
	v_lshl_add_u64 v[2:3], s[2:3], 0, v[2:3]
	global_load_dword v49, v[4:5], off
	global_load_dword v38, v[2:3], off
	v_min_i32_e32 v2, v43, v0
	v_ashrrev_i32_e32 v3, 31, v2
	v_lshlrev_b64 v[2:3], 2, v[2:3]
	v_lshl_add_u64 v[4:5], s[4:5], 0, v[2:3]
	v_lshl_add_u64 v[2:3], s[2:3], 0, v[2:3]
	global_load_dword v45, v[4:5], off
	global_load_dword v36, v[2:3], off
	v_min_i32_e32 v2, v39, v0
	v_ashrrev_i32_e32 v3, 31, v2
	v_min_i32_e32 v0, v35, v0
	v_lshlrev_b64 v[2:3], 2, v[2:3]
	v_ashrrev_i32_e32 v1, 31, v0
	v_lshl_add_u64 v[4:5], s[4:5], 0, v[2:3]
	v_lshl_add_u64 v[2:3], s[2:3], 0, v[2:3]
	v_lshlrev_b64 v[0:1], 2, v[0:1]
	global_load_dword v41, v[4:5], off
	global_load_dword v34, v[2:3], off
	v_lshl_add_u64 v[2:3], s[4:5], 0, v[0:1]
	v_lshl_add_u64 v[0:1], s[2:3], 0, v[0:1]
	global_load_dword v37, v[2:3], off
	global_load_dword v32, v[0:1], off
	v_mov_b32_e32 v0, v172
	v_accvgpr_write_b32 a112, 0
	v_lshlrev_b32_e32 v1, 3, v0
	v_and_b32_e32 v2, 48, v0
	v_bitop3_b32 v1, v1, v2, s37 bitop3:0x6c
	v_lshlrev_b32_e32 v2, 7, v0
	v_and_b32_e32 v3, 0xffffc780, v2
	v_and_b32_e32 v2, 0x2780, v2
	v_or_b32_e32 v4, v1, v2
	v_or_b32_e32 v156, v1, v3
	v_or_b32_e32 v157, 0x8000, v4
	v_lshlrev_b32_e32 v158, 4, v0
	v_bitop3_b32 v159, v1, 64, v3 bitop3:0x36
	v_bitop3_b32 v160, v1, s1, v2 bitop3:0x36
	v_accvgpr_write_b32 a127, 0
	v_accvgpr_write_b32 a126, 0
	v_accvgpr_write_b32 a125, 0
	v_accvgpr_write_b32 a124, 0
	v_accvgpr_write_b32 a123, 0
	v_accvgpr_write_b32 a122, 0
	v_accvgpr_write_b32 a121, 0
	v_accvgpr_write_b32 a120, 0
	v_accvgpr_write_b32 a119, 0
	v_accvgpr_write_b32 a118, 0
	v_accvgpr_write_b32 a117, 0
	v_accvgpr_write_b32 a116, 0
	v_accvgpr_write_b32 a111, 0
	v_accvgpr_write_b32 a110, 0
	v_accvgpr_write_b32 a109, 0
	v_accvgpr_write_b32 a108, 0
	v_accvgpr_write_b32 a107, 0
	v_accvgpr_write_b32 a106, 0
	v_accvgpr_write_b32 a105, 0
	v_accvgpr_write_b32 a104, 0
	v_accvgpr_write_b32 a103, 0
	v_accvgpr_write_b32 a102, 0
	v_accvgpr_write_b32 a101, 0
	v_accvgpr_write_b32 a100, 0
	v_accvgpr_write_b32 a95, 0
	v_accvgpr_write_b32 a94, 0
	v_accvgpr_write_b32 a93, 0
	v_accvgpr_write_b32 a92, 0
	v_accvgpr_write_b32 a91, 0
	v_accvgpr_write_b32 a90, 0
	v_accvgpr_write_b32 a89, 0
	v_accvgpr_write_b32 a88, 0
	v_accvgpr_write_b32 a87, 0
	v_accvgpr_write_b32 a86, 0
	v_accvgpr_write_b32 a85, 0
	v_accvgpr_write_b32 a84, 0
	v_accvgpr_write_b32 a79, 0
	v_accvgpr_write_b32 a78, 0
	v_accvgpr_write_b32 a77, 0
	v_accvgpr_write_b32 a76, 0
	v_accvgpr_write_b32 a75, 0
	v_accvgpr_write_b32 a74, 0
	v_accvgpr_write_b32 a73, 0
	v_accvgpr_write_b32 a72, 0
	v_accvgpr_write_b32 a71, 0
	v_accvgpr_write_b32 a70, 0
	v_accvgpr_write_b32 a69, 0
	v_accvgpr_write_b32 a68, 0
	v_accvgpr_write_b32 a63, 0
	v_accvgpr_write_b32 a62, 0
	v_accvgpr_write_b32 a61, 0
	v_accvgpr_write_b32 a60, 0
	v_accvgpr_write_b32 a59, 0
	v_accvgpr_write_b32 a58, 0
	v_accvgpr_write_b32 a57, 0
	v_accvgpr_write_b32 a56, 0
	v_accvgpr_write_b32 a55, 0
	v_accvgpr_write_b32 a54, 0
	v_accvgpr_write_b32 a53, 0
	v_accvgpr_write_b32 a52, 0
	v_accvgpr_write_b32 a47, 0
	v_accvgpr_write_b32 a46, 0
	v_accvgpr_write_b32 a45, 0
	v_accvgpr_write_b32 a44, 0
	v_accvgpr_write_b32 a43, 0
	v_accvgpr_write_b32 a42, 0
	v_accvgpr_write_b32 a41, 0
	v_accvgpr_write_b32 a40, 0
	v_accvgpr_write_b32 a39, 0
	v_accvgpr_write_b32 a38, 0
	v_accvgpr_write_b32 a37, 0
	v_accvgpr_write_b32 a36, 0
	v_accvgpr_write_b32 a31, 0
	v_accvgpr_write_b32 a30, 0
	v_accvgpr_write_b32 a29, 0
	v_accvgpr_write_b32 a28, 0
	v_accvgpr_write_b32 a27, 0
	v_accvgpr_write_b32 a26, 0
	v_accvgpr_write_b32 a25, 0
	v_accvgpr_write_b32 a24, 0
	v_accvgpr_write_b32 a23, 0
	v_accvgpr_write_b32 a22, 0
	v_accvgpr_write_b32 a21, 0
	v_accvgpr_write_b32 a20, 0
	v_accvgpr_write_b32 a15, 0
	v_accvgpr_write_b32 a14, 0
	v_accvgpr_write_b32 a13, 0
	v_accvgpr_write_b32 a12, 0
	s_mov_b32 s1, 0
	s_mov_b64 s[2:3], 0
	s_mov_b32 s7, 0
	v_readfirstlane_b32 s100, v158
	s_waitcnt vmcnt(44)
	s_barrier
	s_add_u32 s101, s100, 0x18000
	v_lshl_add_u64 v[10:11], v[26:27], 0, s[2:3]
	s_add_u32 m0, s101, 0x0
	v_lshl_add_u64 v[14:15], v[10:11], 0, s[74:75]
	global_load_lds_dwordx4 v[14:15], off
	s_add_u32 m0, s101, 0x1000
	v_lshl_add_u64 v[14:15], v[10:11], 0, s[24:25]
	global_load_lds_dwordx4 v[14:15], off
	s_add_u32 m0, s101, 0x2000
	v_lshl_add_u64 v[14:15], v[10:11], 0, s[76:77]
	global_load_lds_dwordx4 v[14:15], off
	s_add_u32 m0, s101, 0x3000
	v_lshl_add_u64 v[14:15], v[10:11], 0, s[26:27]
	global_load_lds_dwordx4 v[14:15], off
	s_add_u32 m0, s101, 0x4000
	v_lshl_add_u64 v[14:15], v[10:11], 0, s[86:87]
	global_load_lds_dwordx4 v[14:15], off
	s_mov_b64 s[4:5], 0x28100
	s_add_u32 m0, s101, 0x5000
	v_lshl_add_u64 v[14:15], v[10:11], 0, s[4:5]
	global_load_lds_dwordx4 v[14:15], off
	ds_read_b128 v[122:125], v157 offset:0
	ds_read_b128 v[126:129], v157 offset:2048
	ds_read_b128 v[130:133], v157 offset:4096
	ds_read_b128 v[134:137], v157 offset:6144
	ds_read_b128 v[90:93], v156 offset:0
	ds_read_b128 v[94:97], v156 offset:2048
	ds_read_b128 v[98:101], v156 offset:4096
	ds_read_b128 v[102:105], v156 offset:6144
	ds_read_b128 v[106:109], v156 offset:8192
	ds_read_b128 v[110:113], v156 offset:10240
	ds_read_b128 v[114:117], v156 offset:12288
	ds_read_b128 v[118:121], v156 offset:14336

; DI void wait_vm0() { asm volatile("s_waitcnt vmcnt(0)" ::: "memory"); }
; template <bool PRE = false, class AF, class BF>
; DI void gemm256(AF aptr, BF bptr, int nk, char* smem, f4 (&acc)[8][4]) {
;     ...
;     if (kt + 1 < nk) asm volatile("s_waitcnt vmcnt(12)" ::: "memory"); else wait_vm0();
.Lg_e2_w12:
	s_cmp_eq_u32 s1, 0
	s_cbranch_scc0 .Lg_e2_w12b
	s_waitcnt vmcnt(44) lgkmcnt(0)
	s_branch .Lg_e2_wd

; DI void moe_e2_phase(const Params& P, int l, char* smem, int* tb) {
;     ...
;   auto ptrs = [&](int rt, int nt, const half_t*& a0, const half_t*& b0) {
;     int e = 0;
;     while (tb[e + 1] <= rt) e++;
;     a0 = P.H + ((size_t)rt * 256 + srow) * 512 + sc;
;     b0 = P.Wt2 + ((size_t)(l * 32 + e) * 1024 + nt * 128 + srow) * 512 + sc;
;   };
;     ...
;     int it2 = it + 1, rt2, nt2;
;     const bool have2 = next_tile(it2, MT, 8, rt2, nt2);
;     const half_t* a1 = a0; const half_t* b1 = b0;
;     if (have2) {
;       asm volatile("" : "+s"(rt2), "+s"(nt2));
;       ptrs(rt2, nt2, a1, b1);
;       gemm_prologue([&](int i) { return a1 + (size_t)i * 32 * 512; }, [&](int i) { return b1 + (size_t)i * 32 * 512; }, 8, smem);
;     }
.LBB0_627:
	s_andn2_b64 vcc, exec, s[4:5]
	s_cbranch_vccnz .LBB0_631
	v_and_b32_e32 v4, 31, v172
	v_lshlrev_b32_e32 v4, 2, v4
	v_add_u32_e32 v4, 0x26004, v4
	ds_read_b32 v4, v4
	s_waitcnt lgkmcnt(0)
	v_cmp_ge_i32_e32 vcc, s0, v4
	s_bcnt1_i32_b32 s4, vcc_lo
	s_lshl_b32 s1, s4, 2
	s_add_i32 s1, s1, 0x26008
.LBB0_629:
	s_add_i32 s84, s4, s20
	s_lshl_b32 s4, s11, 7
	s_ashr_i32 s1, s0, 31
	s_ashr_i32 s5, s4, 31
	v_mov_b32_e32 v4, v172
	s_lshl_b64 s[22:23], s[0:1], 18
	v_lshl_add_u64 v[28:29], s[4:5], 0, v[24:25]
	s_lshl_b64 s[4:5], s[84:85], 20
	v_readlane_b32 s1, v253, 57
	s_add_u32 s4, s1, s4
	v_readlane_b32 s1, v253, 58
	v_lshlrev_b32_e32 v4, 4, v4
	s_addc_u32 s5, s1, s5
	v_readfirstlane_b32 s1, v4
	v_add_u32_e32 v14, 0x1000, v4
	v_lshl_add_u64 v[26:27], v[30:31], 0, s[22:23]
	s_mov_b32 m0, s1
	s_mov_b64 s[22:23], 0x8000
	v_readfirstlane_b32 s1, v14
	v_add_u32_e32 v14, 0x2000, v4
	global_load_lds_dwordx4 v[26:27], off
	v_lshl_add_u64 v[156:157], v[26:27], 0, s[22:23]
	s_mov_b32 m0, s1
	v_readfirstlane_b32 s1, v14
	v_add_u32_e32 v14, 0x3000, v4
	v_lshlrev_b64 v[28:29], 10, v[28:29]
	global_load_lds_dwordx4 v[156:157], off
	v_lshl_add_u64 v[156:157], v[26:27], 0, s[68:69]
	s_mov_b32 m0, s1
	s_mov_b64 s[34:35], 0x18000
	v_readfirstlane_b32 s1, v14
	v_add_u32_e32 v14, 0x4000, v4
	v_lshl_add_u64 v[28:29], s[4:5], 0, v[28:29]
	global_load_lds_dwordx4 v[156:157], off
	v_lshl_add_u64 v[156:157], v[26:27], 0, s[34:35]
	s_mov_b32 m0, s1
	s_mov_b64 s[4:5], 0x20000
	v_readfirstlane_b32 s1, v14
	v_add_u32_e32 v14, 0x5000, v4
	global_load_lds_dwordx4 v[156:157], off
	v_lshl_add_u64 v[156:157], v[26:27], 0, s[4:5]
	s_mov_b32 m0, s1
	s_mov_b64 s[4:5], 0x28000
	v_readfirstlane_b32 s1, v14
	v_add_u32_e32 v14, 0x6000, v4
	global_load_lds_dwordx4 v[156:157], off
	v_lshl_add_u64 v[156:157], v[26:27], 0, s[4:5]
	s_mov_b32 m0, s1
	s_mov_b64 s[4:5], 0x30000
	v_readfirstlane_b32 s1, v14
	v_add_u32_e32 v14, 0x7000, v4
	global_load_lds_dwordx4 v[156:157], off
	v_lshl_add_u64 v[156:157], v[26:27], 0, s[4:5]
	s_mov_b32 m0, s1
	s_mov_b64 s[4:5], 0x38000
	v_readfirstlane_b32 s1, v14
	v_add_u32_e32 v14, 0x8000, v4
	global_load_lds_dwordx4 v[156:157], off
	v_lshl_add_u64 v[156:157], v[26:27], 0, s[4:5]
	s_mov_b32 m0, s1
	v_readfirstlane_b32 s1, v14
	v_add_u32_e32 v14, 0x9000, v4
	v_lshl_add_u64 v[28:29], v[28:29], 0, v[148:149]
	global_load_lds_dwordx4 v[156:157], off
	s_mov_b32 m0, s1
	v_readfirstlane_b32 s1, v14
	v_add_u32_e32 v14, 0xa000, v4
	global_load_lds_dwordx4 v[28:29], off
	v_lshl_add_u64 v[156:157], v[28:29], 0, s[22:23]
	s_mov_b32 m0, s1
	v_readfirstlane_b32 s1, v14
	v_add_u32_e32 v14, 0xb000, v4
	global_load_lds_dwordx4 v[156:157], off
	v_lshl_add_u64 v[156:157], v[28:29], 0, s[68:69]
	s_mov_b32 m0, s1
	v_readfirstlane_b32 s1, v14
	v_add_u32_e32 v14, 0xc000, v4
	global_load_lds_dwordx4 v[156:157], off
	v_lshl_add_u64 v[156:157], v[28:29], 0, s[34:35]
	s_mov_b32 m0, s1
	v_readfirstlane_b32 s1, v14
	v_add_u32_e32 v14, 0xd000, v4
	global_load_lds_dwordx4 v[156:157], off
	v_lshl_add_u64 v[156:157], v[26:27], 0, s[92:93]
	s_mov_b32 m0, s1
	s_mov_b64 s[34:35], 0x8080
	v_readfirstlane_b32 s1, v14
	v_add_u32_e32 v14, 0xe000, v4
	global_load_lds_dwordx4 v[156:157], off
	v_lshl_add_u64 v[156:157], v[26:27], 0, s[34:35]
	s_mov_b32 m0, s1
	s_mov_b64 s[4:5], 0x10080
	v_readfirstlane_b32 s1, v14
	v_add_u32_e32 v14, 0xf000, v4
	global_load_lds_dwordx4 v[156:157], off
	v_lshl_add_u64 v[156:157], v[26:27], 0, s[4:5]
	s_mov_b32 m0, s1
	s_mov_b64 s[38:39], 0x18080
	v_readfirstlane_b32 s1, v14
	v_add_u32_e32 v14, 0x10000, v4
	global_load_lds_dwordx4 v[156:157], off
	v_lshl_add_u64 v[156:157], v[26:27], 0, s[38:39]
	s_mov_b32 m0, s1
	s_mov_b64 s[22:23], 0x20080
	v_readfirstlane_b32 s1, v14
	v_add_u32_e32 v14, 0x11000, v4
	global_load_lds_dwordx4 v[156:157], off
	v_lshl_add_u64 v[156:157], v[26:27], 0, s[22:23]
	s_mov_b32 m0, s1
	s_mov_b64 s[22:23], 0x28080
	v_readfirstlane_b32 s1, v14
	v_add_u32_e32 v14, 0x12000, v4
	global_load_lds_dwordx4 v[156:157], off
	v_lshl_add_u64 v[156:157], v[26:27], 0, s[22:23]
	s_mov_b32 m0, s1
	s_mov_b64 s[22:23], 0x30080
	v_readfirstlane_b32 s1, v14
	v_add_u32_e32 v14, 0x13000, v4
	global_load_lds_dwordx4 v[156:157], off
	v_lshl_add_u64 v[156:157], v[26:27], 0, s[22:23]
	s_mov_b32 m0, s1
	s_mov_b64 s[22:23], 0x38080
	v_readfirstlane_b32 s1, v14
	v_add_u32_e32 v14, 0x14000, v4
	global_load_lds_dwordx4 v[156:157], off
	v_lshl_add_u64 v[156:157], v[26:27], 0, s[22:23]
	s_mov_b32 m0, s1
	v_readfirstlane_b32 s1, v14
	v_add_u32_e32 v14, 0x15000, v4
	global_load_lds_dwordx4 v[156:157], off
	v_lshl_add_u64 v[156:157], v[28:29], 0, s[92:93]
	s_mov_b32 m0, s1
	v_readfirstlane_b32 s1, v14
	v_add_u32_e32 v14, 0x16000, v4
	global_load_lds_dwordx4 v[156:157], off
	v_lshl_add_u64 v[156:157], v[28:29], 0, s[34:35]
	s_mov_b32 m0, s1
	v_readfirstlane_b32 s1, v14
	v_add_u32_e32 v4, 0x17000, v4
	global_load_lds_dwordx4 v[156:157], off
	v_lshl_add_u64 v[156:157], v[28:29], 0, s[4:5]
	s_mov_b32 m0, s1
	v_readfirstlane_b32 s1, v4
	global_load_lds_dwordx4 v[156:157], off
	v_lshl_add_u64 v[156:157], v[28:29], 0, s[38:39]
	s_mov_b32 m0, s1
	s_nop 0
	global_load_lds_dwordx4 v[156:157], off
